# barrier edits + P2 plain stores + P5 ACT stores plain (no nt)
# baseline (speedup 1.0000x reference)
;     __device__ __forceinline__ void run(f32x4 (&acc)[2][2][4][2], const pg8::Unit& u, int wr, int wc, int fr_, int fq_, int buf) const {
;     ...
;         {   f32x4 rs[2];
; #pragma unroll
;             for (int ai = 0; ai < 2; ++ai) { const f32x4 q = *(const LAS f32x4*)(T + 128 * ai + 64 * wr + 4 * fr);
;                 rs[ai][0] = rsqrtf(q[0] * (1.0f / D) + EPS); rs[ai][1] = rsqrtf(q[1] * (1.0f / D) + EPS); rs[ai][2] = rsqrtf(q[2] * (1.0f / D) + EPS); rs[ai][3] = rsqrtf(q[3] * (1.0f / D) + EPS); }
; #pragma unroll
;             for (int bj = 0; bj < 2; ++bj)
; #pragma unroll
;                 for (int n = 0; n < 2; ++n) { const f32x4 c2v = *(const LAS f32x4*)(T + 256 + 128 * bj + colL + 4 * n);
; #pragma unroll
;                     for (int ai = 0; ai < 2; ++ai)
; #pragma unroll
;                         for (int m = 0; m < 4; ++m) acc[ai][bj][m][n] = acc[ai][bj][m][n] * rs[ai][m] + c2v; } }
;         if (fr == 0 || fr == 15) {
;             const bool lastr = fr == 15;
;             LAS float* xb = X + (lastr ? 256 : 0) + colL;
; #pragma unroll
;             for (int bj = 0; bj < 2; ++bj)
; #pragma unroll
;                 for (int n = 0; n < 2; ++n)
; #pragma unroll
;                     for (int ai = 0; ai < 2; ++ai) { const int rb = 2 * ai + wr; f32x4 v;
; #pragma unroll
;                         for (int e = 0; e < 4; ++e) v[e] = lastr ? acc[ai][bj][3][n][e] : acc[ai][bj][0][n][e];
;                         *(LAS f32x4*)(xb + rb * 512 + 128 * bj + 4 * n) = v; }
;         }
;         asm volatile("s_waitcnt lgkmcnt(0)" ::: "memory"); __builtin_amdgcn_s_barrier(); asm volatile("" ::: "memory");
;         if (wr == 0 && fr == 0) {
; #pragma unroll
;             for (int bj = 0; bj < 2; ++bj)
; #pragma unroll
;                 for (int n = 0; n < 2; ++n) { float* ep = edge + ((size_t)gpm * 4 + 0) * FF2 + colg + 128 * bj + 4 * n; *(f32x4*)ep = acc[0][bj][0][n]; *(f32x4*)(ep + FF2) = acc[0][bj][1][n]; }
;         }
;         if (wr == 1 && fr == 15) {
; #pragma unroll
;             for (int bj = 0; bj < 2; ++bj)
; #pragma unroll
;                 for (int n = 0; n < 2; ++n) { float* ep = edge + ((size_t)gpm * 4 + 2) * FF2 + colg + 128 * bj + 4 * n; *(f32x4*)ep = acc[1][bj][2][n]; *(f32x4*)(ep + FF2) = acc[1][bj][3][n]; }
;         }
;         typedef float f32x2 __attribute__((ext_vector_type(2)));
; #pragma unroll
.LBB0_545:
	s_or_b64 exec, exec, s[0:1]
	v_fmamk_f32 v70, v152, 0x3a800000, v233
	v_mul_f32_e32 v71, 0x4b800000, v70
	v_cmp_gt_f32_e32 vcc, s81, v70
	v_lshl_add_u32 v238, v236, 2, s42
	v_and_b32_e32 v236, 56, v146
	v_cndmask_b32_e32 v70, v70, v71, vcc
	v_fmamk_f32 v71, v147, 0x3a800000, v233
	v_mul_f32_e32 v72, 0x4b800000, v71
	v_cmp_gt_f32_e64 s[0:1], s81, v71
	v_rsq_f32_e32 v70, v70
	s_nop 0
	v_cndmask_b32_e64 v71, v71, v72, s[0:1]
	v_rsq_f32_e32 v71, v71
	v_mul_f32_e32 v72, 0x45800000, v70
	v_cndmask_b32_e32 v70, v70, v72, vcc
	s_andn2_b64 vcc, exec, s[50:51]
	v_mul_f32_e32 v72, 0x45800000, v71
	v_cndmask_b32_e64 v72, v71, v72, s[0:1]
	v_pk_fma_f32 v[224:225], v[60:61], v[70:71], v[144:145] op_sel_hi:[1,0,1]
	v_pk_fma_f32 v[58:59], v[58:59], v[70:71], v[142:143] op_sel_hi:[1,0,1]
	v_pk_fma_f32 v[216:217], v[56:57], v[70:71], v[140:141] op_sel_hi:[1,0,1]
	v_pk_fma_f32 v[220:221], v[54:55], v[70:71], v[138:139] op_sel_hi:[1,0,1]
	v_pk_fma_f32 v[222:223], v[44:45], v[70:71], v[136:137] op_sel_hi:[1,0,1]
	v_pk_fma_f32 v[226:227], v[42:43], v[70:71], v[134:135] op_sel_hi:[1,0,1]
	v_pk_fma_f32 v[214:215], v[36:37], v[70:71], v[132:133] op_sel_hi:[1,0,1]
	v_pk_fma_f32 v[218:219], v[34:35], v[70:71], v[130:131] op_sel_hi:[1,0,1]
	v_add_u32_e32 v70, s68, v239
	v_pk_fma_f32 v[184:185], v[38:39], v[72:73], v[142:143] op_sel_hi:[1,0,1]
	v_pk_fma_f32 v[190:191], v[40:41], v[72:73], v[144:145] op_sel_hi:[1,0,1]
	ds_read_b128 v[142:145], v70
	s_lshl_b32 s1, s52, 7
	v_pk_fma_f32 v[192:193], v[10:11], v[72:73], v[130:131] op_sel_hi:[1,0,1]
	v_subrev_u32_e32 v10, s1, v82
	v_add_u32_e32 v71, s69, v239
	v_pk_fma_f32 v[194:195], v[26:27], v[72:73], v[138:139] op_sel_hi:[1,0,1]
	v_pk_fma_f32 v[200:201], v[28:29], v[72:73], v[140:141] op_sel_hi:[1,0,1]
	v_pk_fma_f32 v[182:183], v[14:15], v[72:73], v[134:135] op_sel_hi:[1,0,1]
	v_pk_fma_f32 v[188:189], v[16:17], v[72:73], v[136:137] op_sel_hi:[1,0,1]
	v_pk_fma_f32 v[202:203], v[12:13], v[72:73], v[132:133] op_sel_hi:[1,0,1]
	v_ashrrev_i32_e32 v237, 6, v10
	ds_read_b128 v[138:141], v71
	ds_read_b128 v[134:137], v70 offset:16
	ds_read_b128 v[130:133], v71 offset:16
	ds_read_b128 v[10:13], v162 offset:5120
	ds_read_b128 v[26:29], v162 offset:2048
	ds_read_b128 v[14:17], v162 offset:4096
	ds_read_b128 v[34:37], v162 offset:3072
	ds_read_b128 v[38:41], v162 offset:2064
	ds_read_b128 v[78:81], v162 offset:5136
	s_waitcnt lgkmcnt(0)
	v_mov_b32_dpp v142, v126 row_shr:1 row_mask:0xf bank_mask:0xf
	v_mov_b32_dpp v143, v127 row_shr:1 row_mask:0xf bank_mask:0xf
	v_pk_fma_f32 v[42:43], v[26:27], v[142:143], v[10:11]
	v_pk_fma_f32 v[44:45], v[118:119], v[26:27], v[10:11]
	v_pk_fma_f32 v[42:43], v[118:119], v[34:35], v[42:43]
	v_pk_fma_f32 v[44:45], v[102:103], v[34:35], v[44:45]
	v_pk_fma_f32 v[42:43], v[102:103], v[14:15], v[42:43]
	v_pk_fma_f32 v[44:45], v[58:59], v[14:15], v[44:45]
	v_exp_f32_e64 v56, -v42
	v_exp_f32_e64 v57, -v43
	v_pk_fma_f32 v[54:55], v[102:103], v[26:27], v[10:11]
	v_exp_f32_e64 v60, -v44
	v_exp_f32_e64 v61, -v45
	v_pk_add_f32 v[56:57], v[56:57], 1.0 op_sel_hi:[1,0]
	v_pk_fma_f32 v[54:55], v[58:59], v[34:35], v[54:55]
	v_rcp_f32_e32 v56, v56
	v_rcp_f32_e32 v57, v57
	v_pk_fma_f32 v[58:59], v[58:59], v[26:27], v[10:11]
	v_mov_b32_dpp v138, v118 row_shl:1 row_mask:0xf bank_mask:0xf
	v_mov_b32_dpp v139, v119 row_shl:1 row_mask:0xf bank_mask:0xf
	v_pk_fma_f32 v[58:59], v[126:127], v[34:35], v[58:59]
	v_pk_fma_f32 v[54:55], v[126:127], v[14:15], v[54:55]
	v_pk_fma_f32 v[58:59], v[14:15], v[138:139], v[58:59]
	v_pk_mul_f32 v[102:103], v[42:43], v[56:57]
	v_pk_add_f32 v[42:43], v[60:61], 1.0 op_sel_hi:[1,0]
	v_exp_f32_e64 v56, -v54
	v_exp_f32_e64 v57, -v55
	v_exp_f32_e64 v60, -v58
	v_exp_f32_e64 v61, -v59
	ds_read_b128 v[82:85], v162 offset:3088
	ds_read_b128 v[240:243], v70 offset:512
	v_pk_add_f32 v[56:57], v[56:57], 1.0 op_sel_hi:[1,0]
	v_pk_add_f32 v[60:61], v[60:61], 1.0 op_sel_hi:[1,0]
	v_rcp_f32_e32 v42, v42
	v_rcp_f32_e32 v43, v43
	v_rcp_f32_e32 v56, v56
	v_rcp_f32_e32 v57, v57
	v_rcp_f32_e32 v60, v60
	v_rcp_f32_e32 v61, v61
	ds_read_b128 v[90:93], v162 offset:4112
	ds_read_b128 v[244:247], v71 offset:512
	ds_read_b128 v[146:149], v70 offset:528
	v_pk_mul_f32 v[138:139], v[44:45], v[42:43]
	v_pk_mul_f32 v[142:143], v[54:55], v[56:57]
	v_pk_mul_f32 v[248:249], v[58:59], v[60:61]
	ds_read_b128 v[150:153], v71 offset:528
	ds_read_b128 v[54:57], v162 offset:5632
	ds_read_b128 v[58:61], v162 offset:2560
	ds_read_b128 v[42:45], v162 offset:4608
	ds_read_b128 v[70:73], v162 offset:3584
	ds_read_b128 v[110:113], v162 offset:5648
	ds_read_b128 v[114:117], v162 offset:2576
	s_waitcnt lgkmcnt(0)
; #define LAS __attribute__((address_space(3)))
;     __device__ __forceinline__ void run(f32x4 (&acc)[2][2][4][2], const pg8::Unit& u, int wr, int wc, int fr_, int fq_, int buf) const {
;     ...
;                     for (int bj = 0; bj < 2; ++bj) { const int col = colg + 128 * bj + 4 * n + 2 * eh;
;                         const int tcol = 128 * bj + colL + 4 * n + 2 * eh;
;                         const f32x2 w0 = *(const LAS f32x2*)(TB + tcol), w1 = *(const LAS f32x2*)(TB + 256 + tcol), w2 = *(const LAS f32x2*)(TB + 512 + tcol), cb = *(const LAS f32x2*)(TB + 768 + tcol);
;                         const int ia = rb > 0 ? (rb - 1) * 2 + 1 : 0, ib = rb < 3 ? (rb + 1) * 2 : 7;
;                         const f32x2 above = *(const LAS f32x2*)(X + ia * 256 + 128 * bj + colL + 4 * n + 2 * eh);
;                         const f32x2 below = *(const LAS f32x2*)(X + ib * 256 + 128 * bj + colL + 4 * n + 2 * eh);
;                         f32x2 U0, U1, U2, U3;
;                         U0[0] = acc[ai][bj][0][n][2 * eh]; U0[1] = acc[ai][bj][0][n][2 * eh + 1]; U1[0] = acc[ai][bj][1][n][2 * eh]; U1[1] = acc[ai][bj][1][n][2 * eh + 1];
;                         U2[0] = acc[ai][bj][2][n][2 * eh]; U2[1] = acc[ai][bj][2][n][2 * eh + 1]; U3[0] = acc[ai][bj][3][n][2 * eh]; U3[1] = acc[ai][bj][3][n][2 * eh + 1];
;                         f32x2 up0, dn3;
;                         up0[0] = dpp_shr1(above[0], U3[0]); up0[1] = dpp_shr1(above[1], U3[1]); dn3[0] = dpp_shl1(below[0], U0[0]); dn3[1] = dpp_shl1(below[1], U0[1]);
;                         f32x2 cv[4];
;                         cv[0] = w2 * U1 + (w1 * U0 + (w0 * up0 + cb));
;                         cv[1] = w2 * U2 + (w1 * U1 + (w0 * U0 + cb));
;                         cv[2] = w2 * U3 + (w1 * U2 + (w0 * U1 + cb));
;                         cv[3] = w2 * dn3 + (w1 * U3 + (w0 * U2 + cb));
;                         if (bj == 0) {
; #pragma unroll
;                             for (int m = 0; m < 4; ++m) {
;                                 f32x2 ex; ex[0] = __builtin_amdgcn_exp2f(-cv[m][0]); ex[1] = __builtin_amdgcn_exp2f(-cv[m][1]);
;                                 const f32x2 den = ex + 1.0f; f32x2 rc; rc[0] = __builtin_amdgcn_rcpf(den[0]); rc[1] = __builtin_amdgcn_rcpf(den[1]);
;                                 sg[m] = cv[m] * rc; }
;                         } else {
; #pragma unroll
	v_mov_b32_dpp v240, v212 row_shr:1 row_mask:0xf bank_mask:0xf
	v_mov_b32_dpp v241, v213 row_shr:1 row_mask:0xf bank_mask:0xf
	v_pk_fma_f32 v[118:119], v[58:59], v[240:241], v[54:55]
	v_mov_b32_dpp v244, v106 row_shl:1 row_mask:0xf bank_mask:0xf
	v_mov_b32_dpp v245, v107 row_shl:1 row_mask:0xf bank_mask:0xf
	v_pk_fma_f32 v[118:119], v[106:107], v[70:71], v[118:119]
	v_pk_fma_f32 v[106:107], v[106:107], v[58:59], v[54:55]
	v_pk_fma_f32 v[118:119], v[98:99], v[42:43], v[118:119]
	v_pk_fma_f32 v[106:107], v[98:99], v[70:71], v[106:107]
	v_pk_fma_f32 v[98:99], v[98:99], v[58:59], v[54:55]
	v_pk_fma_f32 v[106:107], v[226:227], v[42:43], v[106:107]
	v_pk_mul_f32 v[102:103], v[102:103], v[118:119]
	v_mov_b32_dpp v144, v208 row_shr:1 row_mask:0xf bank_mask:0xf
	v_mov_b32_dpp v145, v209 row_shr:1 row_mask:0xf bank_mask:0xf
	v_pk_fma_f32 v[98:99], v[226:227], v[70:71], v[98:99]
	v_cvt_pk_bf16_f32 v118, v102, v103
	v_pk_mul_f32 v[102:103], v[138:139], v[106:107]
	v_pk_fma_f32 v[138:139], v[28:29], v[144:145], v[12:13]
	v_pk_fma_f32 v[98:99], v[212:213], v[42:43], v[98:99]
	v_mov_b32_dpp v140, v120 row_shl:1 row_mask:0xf bank_mask:0xf
	v_mov_b32_dpp v141, v121 row_shl:1 row_mask:0xf bank_mask:0xf
	v_pk_fma_f32 v[138:139], v[120:121], v[36:37], v[138:139]
	v_pk_fma_f32 v[120:121], v[120:121], v[28:29], v[12:13]
	v_pk_mul_f32 v[98:99], v[142:143], v[98:99]
	v_pk_fma_f32 v[120:121], v[104:105], v[36:37], v[120:121]
	v_pk_fma_f32 v[142:143], v[224:225], v[28:29], v[12:13]
	v_pk_fma_f32 v[120:121], v[224:225], v[16:17], v[120:121]
	v_pk_fma_f32 v[142:143], v[208:209], v[36:37], v[142:143]
	v_pk_fma_f32 v[138:139], v[104:105], v[16:17], v[138:139]
	v_pk_fma_f32 v[140:141], v[16:17], v[140:141], v[142:143]
	v_exp_f32_e64 v142, -v120
	v_exp_f32_e64 v143, -v121
	v_pk_fma_f32 v[104:105], v[104:105], v[28:29], v[12:13]
	v_pk_fma_f32 v[226:227], v[226:227], v[58:59], v[54:55]
	v_pk_fma_f32 v[104:105], v[224:225], v[36:37], v[104:105]
	v_pk_fma_f32 v[212:213], v[212:213], v[70:71], v[226:227]
	v_pk_fma_f32 v[104:105], v[208:209], v[16:17], v[104:105]
	v_exp_f32_e64 v144, -v138
	v_exp_f32_e64 v145, -v139
	v_pk_fma_f32 v[212:213], v[42:43], v[244:245], v[212:213]
	v_pk_add_f32 v[142:143], v[142:143], 1.0 op_sel_hi:[1,0]
	v_exp_f32_e64 v208, -v104
	v_exp_f32_e64 v209, -v105
	v_cvt_pk_bf16_f32 v106, v102, v103
	v_cvt_pk_bf16_f32 v102, v98, v99
	v_pk_mul_f32 v[98:99], v[248:249], v[212:213]
	v_rcp_f32_e32 v142, v142
	v_rcp_f32_e32 v143, v143
	v_exp_f32_e64 v212, -v140
	v_exp_f32_e64 v213, -v141
	v_pk_add_f32 v[144:145], v[144:145], 1.0 op_sel_hi:[1,0]
	v_pk_add_f32 v[208:209], v[208:209], 1.0 op_sel_hi:[1,0]
	v_rcp_f32_e32 v144, v144
	v_rcp_f32_e32 v145, v145
	v_mov_b32_dpp v242, v210 row_shr:1 row_mask:0xf bank_mask:0xf
	v_mov_b32_dpp v243, v211 row_shr:1 row_mask:0xf bank_mask:0xf
	v_rcp_f32_e32 v208, v208
	v_rcp_f32_e32 v209, v209
	v_pk_add_f32 v[212:213], v[212:213], 1.0 op_sel_hi:[1,0]
	v_pk_mul_f32 v[120:121], v[120:121], v[142:143]
	v_pk_fma_f32 v[142:143], v[60:61], v[242:243], v[56:57]
	v_rcp_f32_e32 v212, v212
	v_rcp_f32_e32 v213, v213
	v_mov_b32_dpp v246, v108 row_shl:1 row_mask:0xf bank_mask:0xf
	v_mov_b32_dpp v247, v109 row_shl:1 row_mask:0xf bank_mask:0xf
	v_pk_fma_f32 v[142:143], v[108:109], v[72:73], v[142:143]
	v_pk_fma_f32 v[108:109], v[108:109], v[60:61], v[56:57]
	v_pk_fma_f32 v[142:143], v[100:101], v[44:45], v[142:143]
	v_pk_fma_f32 v[108:109], v[100:101], v[72:73], v[108:109]
	v_pk_fma_f32 v[100:101], v[100:101], v[60:61], v[56:57]
	v_pk_mul_f32 v[138:139], v[138:139], v[144:145]
	v_pk_fma_f32 v[100:101], v[222:223], v[72:73], v[100:101]
	v_pk_fma_f32 v[144:145], v[222:223], v[60:61], v[56:57]
	v_pk_mul_f32 v[104:105], v[104:105], v[208:209]
	v_pk_fma_f32 v[100:101], v[210:211], v[44:45], v[100:101]
	v_pk_fma_f32 v[144:145], v[210:211], v[72:73], v[144:145]
	v_pk_mul_f32 v[140:141], v[140:141], v[212:213]
	v_pk_fma_f32 v[144:145], v[44:45], v[246:247], v[144:145]
	v_pk_mul_f32 v[100:101], v[104:105], v[100:101]
	v_mov_b32_dpp v134, v204 row_shr:1 row_mask:0xf bank_mask:0xf
	v_cvt_pk_bf16_f32 v103, v100, v101
	v_pk_mul_f32 v[100:101], v[140:141], v[144:145]
	v_mov_b32_dpp v135, v205 row_shr:1 row_mask:0xf bank_mask:0xf
	v_cvt_pk_bf16_f32 v98, v98, v99
	v_cvt_pk_bf16_f32 v99, v100, v101
	v_pk_fma_f32 v[100:101], v[38:39], v[134:135], v[78:79]
	v_mov_b32_dpp v130, v94 row_shl:1 row_mask:0xf bank_mask:0xf
	v_mov_b32_dpp v131, v95 row_shl:1 row_mask:0xf bank_mask:0xf
	v_pk_fma_f32 v[100:101], v[94:95], v[82:83], v[100:101]
	v_pk_fma_f32 v[94:95], v[94:95], v[38:39], v[78:79]
	v_pk_fma_f32 v[100:101], v[74:75], v[90:91], v[100:101]
	v_pk_fma_f32 v[94:95], v[74:75], v[82:83], v[94:95]
	v_pk_fma_f32 v[74:75], v[74:75], v[38:39], v[78:79]
	v_pk_fma_f32 v[104:105], v[220:221], v[38:39], v[78:79]
	v_pk_fma_f32 v[74:75], v[220:221], v[82:83], v[74:75]
	v_pk_fma_f32 v[104:105], v[204:205], v[82:83], v[104:105]
	v_pk_fma_f32 v[74:75], v[204:205], v[90:91], v[74:75]
	v_pk_fma_f32 v[104:105], v[90:91], v[130:131], v[104:105]
	v_exp_f32_e64 v130, -v74
	v_exp_f32_e64 v131, -v75
	v_exp_f32_e64 v134, -v104
	v_exp_f32_e64 v135, -v105
	v_pk_fma_f32 v[108:109], v[222:223], v[44:45], v[108:109]
	v_pk_add_f32 v[130:131], v[130:131], 1.0 op_sel_hi:[1,0]
	v_pk_mul_f32 v[108:109], v[120:121], v[108:109]
	v_pk_add_f32 v[134:135], v[134:135], 1.0 op_sel_hi:[1,0]
	v_cvt_pk_bf16_f32 v107, v108, v109
	v_exp_f32_e64 v108, -v100
	v_exp_f32_e64 v109, -v101
	ds_read_b128 v[122:125], v162 offset:3600
	ds_read_b128 v[126:129], v162 offset:4624
	v_rcp_f32_e32 v130, v130
	v_rcp_f32_e32 v131, v131
	v_rcp_f32_e32 v134, v134
	v_rcp_f32_e32 v135, v135
	v_pk_fma_f32 v[94:95], v[220:221], v[90:91], v[94:95]
	v_pk_add_f32 v[108:109], v[108:109], 1.0 op_sel_hi:[1,0]
	v_exp_f32_e64 v120, -v94
	v_exp_f32_e64 v121, -v95
	v_rcp_f32_e32 v108, v108
	v_rcp_f32_e32 v109, v109
	v_mov_b32_dpp v146, v206 row_shr:1 row_mask:0xf bank_mask:0xf
	v_mov_b32_dpp v147, v207 row_shr:1 row_mask:0xf bank_mask:0xf
	v_pk_mul_f32 v[74:75], v[74:75], v[130:131]
	v_pk_mul_f32 v[130:131], v[104:105], v[134:135]
	v_pk_fma_f32 v[104:105], v[114:115], v[146:147], v[110:111]
	v_mov_b32_dpp v150, v86 row_shl:1 row_mask:0xf bank_mask:0xf
	v_mov_b32_dpp v151, v87 row_shl:1 row_mask:0xf bank_mask:0xf
	s_waitcnt lgkmcnt(0)
; __device__ __forceinline__ unsigned cvt_pk(float lo, float hi) { f32x2_t v = {lo, hi}; bf16x2_t b = __builtin_convertvector(v, bf16x2_t); return __builtin_bit_cast(unsigned, b); }
; __device__ __forceinline__ size_t blk_off(int row, int col, int K) { return ((size_t)((row >> 8) * (K >> 6) + (col >> 6)) << 14) + (size_t)(((row & 255) << 6) + (col & 63)); }
;     __device__ __forceinline__ void run(f32x4 (&acc)[2][2][4][2], const pg8::Unit& u, int wr, int wc, int fr_, int fq_, int buf) const {
;     ...
;                         cv[0] = w2 * U1 + (w1 * U0 + (w0 * up0 + cb));
;                         cv[1] = w2 * U2 + (w1 * U1 + (w0 * U0 + cb));
;                         cv[2] = w2 * U3 + (w1 * U2 + (w0 * U1 + cb));
;                         cv[3] = w2 * dn3 + (w1 * U3 + (w0 * U2 + cb));
;                         if (bj == 0) {
; #pragma unroll
;                             for (int m = 0; m < 4; ++m) {
;                                 f32x2 ex; ex[0] = __builtin_amdgcn_exp2f(-cv[m][0]); ex[1] = __builtin_amdgcn_exp2f(-cv[m][1]);
;                                 const f32x2 den = ex + 1.0f; f32x2 rc; rc[0] = __builtin_amdgcn_rcpf(den[0]); rc[1] = __builtin_amdgcn_rcpf(den[1]);
;                                 sg[m] = cv[m] * rc; }
;                         } else {
; #pragma unroll
;                             for (int m = 0; m < 4; ++m) { const f32x2 av = sg[m] * cv[m]; pk[m][n][eh] = cvt_pk(av[0], av[1]); }
;                         }
;                     }
;                 }
;             }
; #pragma unroll
;             for (int m = 0; m < 4; ++m) { const int tr = 128 * ai + 64 * wr + 4 * fr + m; v4u w; w.x = pk[m][0][0]; w.y = pk[m][0][1]; w.z = pk[m][1][0]; w.w = pk[m][1][1];
;                 __builtin_nontemporal_store(w, (v4u*)(act + blk_off(u.pm * 256 + tr, u.pn * 128 + colL, FF))); }
	v_pk_fma_f32 v[104:105], v[86:87], v[122:123], v[104:105]
	v_pk_fma_f32 v[86:87], v[86:87], v[114:115], v[110:111]
	v_pk_add_f32 v[120:121], v[120:121], 1.0 op_sel_hi:[1,0]
	v_pk_fma_f32 v[104:105], v[66:67], v[126:127], v[104:105]
	v_pk_fma_f32 v[86:87], v[66:67], v[122:123], v[86:87]
	v_pk_fma_f32 v[66:67], v[66:67], v[114:115], v[110:111]
	v_rcp_f32_e32 v120, v120
	v_rcp_f32_e32 v121, v121
	v_pk_mul_f32 v[100:101], v[100:101], v[108:109]
	v_pk_fma_f32 v[66:67], v[218:219], v[122:123], v[66:67]
	v_pk_fma_f32 v[108:109], v[218:219], v[114:115], v[110:111]
	v_pk_fma_f32 v[66:67], v[206:207], v[126:127], v[66:67]
	v_pk_fma_f32 v[108:109], v[206:207], v[122:123], v[108:109]
	v_pk_mul_f32 v[66:67], v[74:75], v[66:67]
	v_pk_fma_f32 v[134:135], v[126:127], v[150:151], v[108:109]
	v_pk_mul_f32 v[100:101], v[100:101], v[104:105]
	v_cvt_pk_bf16_f32 v104, v66, v67
	v_pk_mul_f32 v[66:67], v[130:131], v[134:135]
	v_mov_b32_dpp v136, v198 row_shr:1 row_mask:0xf bank_mask:0xf
	v_mov_b32_dpp v137, v199 row_shr:1 row_mask:0xf bank_mask:0xf
	v_pk_mul_f32 v[94:95], v[94:95], v[120:121]
	v_pk_fma_f32 v[86:87], v[218:219], v[126:127], v[86:87]
	v_cvt_pk_bf16_f32 v120, v100, v101
	v_cvt_pk_bf16_f32 v100, v66, v67
	v_pk_fma_f32 v[66:67], v[40:41], v[136:137], v[80:81]
	v_pk_mul_f32 v[86:87], v[94:95], v[86:87]
	v_pk_fma_f32 v[66:67], v[96:97], v[84:85], v[66:67]
	v_cvt_pk_bf16_f32 v108, v86, v87
	v_pk_fma_f32 v[66:67], v[76:77], v[92:93], v[66:67]
	v_pk_fma_f32 v[74:75], v[96:97], v[40:41], v[80:81]
	v_pk_fma_f32 v[86:87], v[216:217], v[40:41], v[80:81]
	v_mov_b32_dpp v132, v96 row_shl:1 row_mask:0xf bank_mask:0xf
	v_mov_b32_dpp v133, v97 row_shl:1 row_mask:0xf bank_mask:0xf
	v_pk_fma_f32 v[74:75], v[76:77], v[84:85], v[74:75]
	v_pk_fma_f32 v[86:87], v[198:199], v[84:85], v[86:87]
	v_exp_f32_e64 v94, -v66
	v_exp_f32_e64 v95, -v67
	v_pk_fma_f32 v[74:75], v[216:217], v[92:93], v[74:75]
	v_pk_fma_f32 v[86:87], v[92:93], v[132:133], v[86:87]
	v_exp_f32_e64 v96, -v74
	v_exp_f32_e64 v97, -v75
	v_exp_f32_e64 v132, -v86
	v_exp_f32_e64 v133, -v87
	v_pk_add_f32 v[94:95], v[94:95], 1.0 op_sel_hi:[1,0]
	v_pk_add_f32 v[96:97], v[96:97], 1.0 op_sel_hi:[1,0]
	v_rcp_f32_e32 v94, v94
	v_rcp_f32_e32 v95, v95
	v_pk_add_f32 v[132:133], v[132:133], 1.0 op_sel_hi:[1,0]
	v_rcp_f32_e32 v96, v96
	v_rcp_f32_e32 v97, v97
	v_rcp_f32_e32 v132, v132
	v_rcp_f32_e32 v133, v133
	v_pk_fma_f32 v[76:77], v[76:77], v[40:41], v[80:81]
	v_pk_mul_f32 v[66:67], v[66:67], v[94:95]
	v_pk_fma_f32 v[76:77], v[216:217], v[84:85], v[76:77]
	v_pk_fma_f32 v[94:95], v[214:215], v[116:117], v[112:113]
	v_pk_fma_f32 v[76:77], v[198:199], v[92:93], v[76:77]
	v_mov_b32_dpp v148, v196 row_shr:1 row_mask:0xf bank_mask:0xf
	v_mov_b32_dpp v149, v197 row_shr:1 row_mask:0xf bank_mask:0xf
	v_mov_b32_dpp v152, v88 row_shl:1 row_mask:0xf bank_mask:0xf
	v_mov_b32_dpp v153, v89 row_shl:1 row_mask:0xf bank_mask:0xf
	v_pk_fma_f32 v[94:95], v[196:197], v[124:125], v[94:95]
	v_exp_f32_e64 v130, -v76
	v_exp_f32_e64 v131, -v77
	v_pk_mul_f32 v[74:75], v[74:75], v[96:97]
	v_pk_mul_f32 v[86:87], v[86:87], v[132:133]
	v_pk_fma_f32 v[94:95], v[128:129], v[152:153], v[94:95]
	v_pk_fma_f32 v[96:97], v[116:117], v[148:149], v[112:113]
	v_pk_mul_f32 v[86:87], v[94:95], v[86:87]
	v_pk_fma_f32 v[94:95], v[88:89], v[116:117], v[112:113]
	v_pk_fma_f32 v[88:89], v[88:89], v[124:125], v[96:97]
	v_cvt_pk_bf16_f32 v101, v86, v87
	v_pk_fma_f32 v[86:87], v[68:69], v[116:117], v[112:113]
	v_pk_fma_f32 v[94:95], v[68:69], v[124:125], v[94:95]
	v_pk_fma_f32 v[68:69], v[68:69], v[128:129], v[88:89]
	s_lshl_b32 s0, s54, 8
	v_pk_mul_f32 v[66:67], v[68:69], v[66:67]
	v_pk_add_f32 v[130:131], v[130:131], 1.0 op_sel_hi:[1,0]
	v_cvt_pk_bf16_f32 v121, v66, v67
	v_add_u32_e32 v66, s0, v238
	v_rcp_f32_e32 v130, v130
	v_rcp_f32_e32 v131, v131
	v_lshrrev_b32_e32 v66, 8, v66
	v_mad_i32_i24 v66, v66, 44, v237
	v_ashrrev_i32_e32 v67, 31, v66
	v_lshlrev_b32_e32 v68, 6, v238
	v_pk_fma_f32 v[86:87], v[214:215], v[124:125], v[86:87]
	v_and_or_b32 v68, v68, s82, v236
	v_lshlrev_b64 v[66:67], 15, v[66:67]
	v_pk_mul_f32 v[138:139], v[138:139], v[142:143]
	v_pk_mul_f32 v[76:77], v[76:77], v[130:131]
	v_pk_fma_f32 v[86:87], v[196:197], v[128:129], v[86:87]
	v_pk_fma_f32 v[94:95], v[214:215], v[128:129], v[94:95]
	v_lshl_add_u64 v[66:67], s[16:17], 0, v[66:67]
	v_lshlrev_b32_e32 v162, 1, v68
	v_cvt_pk_bf16_f32 v119, v138, v139
	v_pk_mul_f32 v[76:77], v[86:87], v[76:77]
	v_pk_mul_f32 v[74:75], v[94:95], v[74:75]
	v_lshl_add_u64 v[66:67], v[66:67], 0, v[162:163]
	v_cvt_pk_bf16_f32 v105, v76, v77
	v_cvt_pk_bf16_f32 v109, v74, v75
	global_store_dwordx4 v[66:67], v[118:121], off
	global_store_dwordx4 v[66:67], v[106:109], off offset:128
	global_store_dwordx4 v[66:67], v[102:105], off offset:256
	global_store_dwordx4 v[66:67], v[98:101], off offset:384
	v_add_u32_e32 v94, s73, v239
	ds_read_b128 v[86:89], v94
	v_add_u32_e32 v95, s74, v239
	ds_read_b128 v[100:103], v94 offset:16
	ds_read_b128 v[96:99], v95
	ds_read_b128 v[104:107], v95 offset:16
	ds_read_b128 v[66:69], v94 offset:512
	ds_read_b128 v[74:77], v95 offset:512
	ds_read_b128 v[118:121], v94 offset:528
	ds_read_b128 v[130:133], v95 offset:528
	v_pk_fma_f32 v[94:95], v[64:65], v[40:41], v[80:81]
	s_waitcnt lgkmcnt(0)
; #define LAS __attribute__((address_space(3)))
;     __device__ __forceinline__ void run(f32x4 (&acc)[2][2][4][2], const pg8::Unit& u, int wr, int wc, int fr_, int fq_, int buf) const {
;     ...
;                     for (int bj = 0; bj < 2; ++bj) { const int col = colg + 128 * bj + 4 * n + 2 * eh;
;                         const int tcol = 128 * bj + colL + 4 * n + 2 * eh;
;                         const f32x2 w0 = *(const LAS f32x2*)(TB + tcol), w1 = *(const LAS f32x2*)(TB + 256 + tcol), w2 = *(const LAS f32x2*)(TB + 512 + tcol), cb = *(const LAS f32x2*)(TB + 768 + tcol);
;                         const int ia = rb > 0 ? (rb - 1) * 2 + 1 : 0, ib = rb < 3 ? (rb + 1) * 2 : 7;
;                         const f32x2 above = *(const LAS f32x2*)(X + ia * 256 + 128 * bj + colL + 4 * n + 2 * eh);
;                         const f32x2 below = *(const LAS f32x2*)(X + ib * 256 + 128 * bj + colL + 4 * n + 2 * eh);
;                         f32x2 U0, U1, U2, U3;
;                         U0[0] = acc[ai][bj][0][n][2 * eh]; U0[1] = acc[ai][bj][0][n][2 * eh + 1]; U1[0] = acc[ai][bj][1][n][2 * eh]; U1[1] = acc[ai][bj][1][n][2 * eh + 1];
;                         U2[0] = acc[ai][bj][2][n][2 * eh]; U2[1] = acc[ai][bj][2][n][2 * eh + 1]; U3[0] = acc[ai][bj][3][n][2 * eh]; U3[1] = acc[ai][bj][3][n][2 * eh + 1];
;                         f32x2 up0, dn3;
;                         up0[0] = dpp_shr1(above[0], U3[0]); up0[1] = dpp_shr1(above[1], U3[1]); dn3[0] = dpp_shl1(below[0], U0[0]); dn3[1] = dpp_shl1(below[1], U0[1]);
;                         f32x2 cv[4];
;                         cv[0] = w2 * U1 + (w1 * U0 + (w0 * up0 + cb));
;                         cv[1] = w2 * U2 + (w1 * U1 + (w0 * U0 + cb));
;                         cv[2] = w2 * U3 + (w1 * U2 + (w0 * U1 + cb));
;                         cv[3] = w2 * dn3 + (w1 * U3 + (w0 * U2 + cb));
;                         if (bj == 0) {
; #pragma unroll
;                             for (int m = 0; m < 4; ++m) {
;                                 f32x2 ex; ex[0] = __builtin_amdgcn_exp2f(-cv[m][0]); ex[1] = __builtin_amdgcn_exp2f(-cv[m][1]);
;                                 const f32x2 den = ex + 1.0f; f32x2 rc; rc[0] = __builtin_amdgcn_rcpf(den[0]); rc[1] = __builtin_amdgcn_rcpf(den[1]);
;                                 sg[m] = cv[m] * rc; }
;                         } else {
; #pragma unroll
	v_mov_b32_dpp v106, v180 row_shl:1 row_mask:0xf bank_mask:0xf
	v_mov_b32_dpp v107, v181 row_shl:1 row_mask:0xf bank_mask:0xf
	v_pk_fma_f32 v[94:95], v[20:21], v[84:85], v[94:95]
	v_mov_b32_dpp v132, v186 row_shl:1 row_mask:0xf bank_mask:0xf
	v_pk_fma_f32 v[94:95], v[92:93], v[106:107], v[94:95]
	v_mov_b32_dpp v133, v187 row_shl:1 row_mask:0xf bank_mask:0xf
	v_exp_f32_e64 v106, -v94
	v_exp_f32_e64 v107, -v95
	v_mov_b32_dpp v120, v24 row_shr:1 row_mask:0xf bank_mask:0xf
	v_mov_b32_dpp v121, v25 row_shr:1 row_mask:0xf bank_mask:0xf
	v_pk_fma_f32 v[108:109], v[200:201], v[40:41], v[80:81]
	v_pk_add_f32 v[106:107], v[106:107], 1.0 op_sel_hi:[1,0]
	v_pk_fma_f32 v[108:109], v[64:65], v[84:85], v[108:109]
	v_rcp_f32_e32 v106, v106
	v_rcp_f32_e32 v107, v107
	v_mov_b32_dpp v102, v20 row_shr:1 row_mask:0xf bank_mask:0xf
	v_mov_b32_dpp v103, v21 row_shr:1 row_mask:0xf bank_mask:0xf
	v_pk_fma_f32 v[20:21], v[20:21], v[92:93], v[108:109]
	v_pk_mul_f32 v[94:95], v[94:95], v[106:107]
	v_pk_fma_f32 v[106:107], v[52:53], v[116:117], v[112:113]
	v_exp_f32_e64 v108, -v20
	v_pk_fma_f32 v[106:107], v[24:25], v[124:125], v[106:107]
	v_exp_f32_e64 v109, -v21
	v_pk_fma_f32 v[106:107], v[128:129], v[132:133], v[106:107]
	v_mov_b32_dpp v104, v176 row_shl:1 row_mask:0xf bank_mask:0xf
	v_pk_mul_f32 v[94:95], v[106:107], v[94:95]
	v_pk_fma_f32 v[106:107], v[202:203], v[116:117], v[112:113]
	v_pk_add_f32 v[108:109], v[108:109], 1.0 op_sel_hi:[1,0]
	v_pk_fma_f32 v[106:107], v[52:53], v[124:125], v[106:107]
	v_rcp_f32_e32 v108, v108
	v_pk_fma_f32 v[24:25], v[24:25], v[128:129], v[106:107]
	v_pk_fma_f32 v[106:107], v[186:187], v[116:117], v[112:113]
	v_rcp_f32_e32 v109, v109
	v_pk_fma_f32 v[106:107], v[202:203], v[124:125], v[106:107]
	v_mov_b32_dpp v105, v177 row_shl:1 row_mask:0xf bank_mask:0xf
	v_pk_fma_f32 v[52:53], v[52:53], v[128:129], v[106:107]
	v_pk_fma_f32 v[106:107], v[116:117], v[120:121], v[112:113]
	v_pk_fma_f32 v[112:113], v[180:181], v[40:41], v[80:81]
	v_pk_fma_f32 v[40:41], v[40:41], v[102:103], v[80:81]
	v_pk_fma_f32 v[112:113], v[200:201], v[84:85], v[112:113]
	v_pk_fma_f32 v[40:41], v[180:181], v[84:85], v[40:41]
	v_pk_fma_f32 v[64:65], v[64:65], v[92:93], v[112:113]
	v_pk_fma_f32 v[40:41], v[200:201], v[92:93], v[40:41]
	v_exp_f32_e64 v112, -v64
	v_exp_f32_e64 v113, -v65
	v_exp_f32_e64 v80, -v40
	v_exp_f32_e64 v81, -v41
	v_pk_mul_f32 v[20:21], v[20:21], v[108:109]
	v_pk_add_f32 v[84:85], v[112:113], 1.0 op_sel_hi:[1,0]
	v_pk_mul_f32 v[20:21], v[24:25], v[20:21]
	v_rcp_f32_e32 v84, v84
	v_rcp_f32_e32 v85, v85
	v_pk_add_f32 v[80:81], v[80:81], 1.0 op_sel_hi:[1,0]
	v_mov_b32_dpp v100, v18 row_shr:1 row_mask:0xf bank_mask:0xf
	v_rcp_f32_e32 v80, v80
	v_pk_mul_f32 v[64:65], v[64:65], v[84:85]
	v_rcp_f32_e32 v81, v81
	v_pk_mul_f32 v[24:25], v[52:53], v[64:65]
	v_pk_fma_f32 v[52:53], v[62:63], v[38:39], v[78:79]
	v_mov_b32_dpp v101, v19 row_shr:1 row_mask:0xf bank_mask:0xf
	v_pk_fma_f32 v[52:53], v[18:19], v[82:83], v[52:53]
	v_pk_mul_f32 v[40:41], v[40:41], v[80:81]
	v_pk_fma_f32 v[52:53], v[90:91], v[104:105], v[52:53]
	v_pk_fma_f32 v[80:81], v[194:195], v[38:39], v[78:79]
	v_exp_f32_e64 v64, -v52
	v_exp_f32_e64 v65, -v53
	v_pk_fma_f32 v[80:81], v[62:63], v[82:83], v[80:81]
	v_pk_fma_f32 v[84:85], v[176:177], v[38:39], v[78:79]
	v_pk_fma_f32 v[18:19], v[18:19], v[90:91], v[80:81]
	v_pk_add_f32 v[64:65], v[64:65], 1.0 op_sel_hi:[1,0]
	v_pk_fma_f32 v[84:85], v[194:195], v[82:83], v[84:85]
	v_rcp_f32_e32 v64, v64
	v_rcp_f32_e32 v65, v65
	v_pk_fma_f32 v[38:39], v[38:39], v[100:101], v[78:79]
	v_exp_f32_e64 v80, -v18
	v_exp_f32_e64 v81, -v19
	v_pk_fma_f32 v[62:63], v[62:63], v[90:91], v[84:85]
	v_pk_fma_f32 v[38:39], v[176:177], v[82:83], v[38:39]
	v_exp_f32_e64 v84, -v62
	v_exp_f32_e64 v85, -v63
	v_pk_fma_f32 v[38:39], v[194:195], v[90:91], v[38:39]
	v_pk_mul_f32 v[52:53], v[52:53], v[64:65]
	v_pk_fma_f32 v[64:65], v[50:51], v[114:115], v[110:111]
	v_mov_b32_dpp v130, v178 row_shl:1 row_mask:0xf bank_mask:0xf
	v_mov_b32_dpp v131, v179 row_shl:1 row_mask:0xf bank_mask:0xf
	v_exp_f32_e64 v78, -v38
	v_exp_f32_e64 v79, -v39
	v_pk_fma_f32 v[64:65], v[22:23], v[122:123], v[64:65]
	v_pk_add_f32 v[80:81], v[80:81], 1.0 op_sel_hi:[1,0]
	v_pk_fma_f32 v[64:65], v[126:127], v[130:131], v[64:65]
	v_cvt_pk_bf16_f32 v95, v94, v95
	v_pk_mul_f32 v[52:53], v[64:65], v[52:53]
	v_rcp_f32_e32 v80, v80
	v_rcp_f32_e32 v81, v81
	v_pk_add_f32 v[82:83], v[84:85], 1.0 op_sel_hi:[1,0]
	v_cvt_pk_bf16_f32 v94, v52, v53
	v_pk_fma_f32 v[52:53], v[192:193], v[114:115], v[110:111]
	v_rcp_f32_e32 v82, v82
	v_rcp_f32_e32 v83, v83
	v_pk_add_f32 v[78:79], v[78:79], 1.0 op_sel_hi:[1,0]
	v_pk_fma_f32 v[52:53], v[50:51], v[122:123], v[52:53]
	v_mov_b32_dpp v118, v22 row_shr:1 row_mask:0xf bank_mask:0xf
	v_mov_b32_dpp v119, v23 row_shr:1 row_mask:0xf bank_mask:0xf
	v_rcp_f32_e32 v78, v78
	v_rcp_f32_e32 v79, v79
	v_pk_fma_f32 v[22:23], v[22:23], v[126:127], v[52:53]
	v_pk_fma_f32 v[52:53], v[178:179], v[114:115], v[110:111]
	v_pk_mul_f32 v[18:19], v[18:19], v[80:81]
	v_pk_fma_f32 v[52:53], v[192:193], v[122:123], v[52:53]
	v_pk_fma_f32 v[106:107], v[186:187], v[124:125], v[106:107]
	v_pk_fma_f32 v[50:51], v[50:51], v[126:127], v[52:53]
	v_pk_fma_f32 v[52:53], v[114:115], v[118:119], v[110:111]
	v_pk_mul_f32 v[62:63], v[62:63], v[82:83]
	v_pk_fma_f32 v[52:53], v[178:179], v[122:123], v[52:53]
	v_pk_mul_f32 v[18:19], v[18:19], v[22:23]
	v_pk_fma_f32 v[92:93], v[202:203], v[128:129], v[106:107]
	v_cvt_pk_bf16_f32 v21, v20, v21
	v_pk_mul_f32 v[38:39], v[38:39], v[78:79]
	v_pk_fma_f32 v[52:53], v[192:193], v[126:127], v[52:53]
	v_cvt_pk_bf16_f32 v20, v18, v19
	v_pk_mul_f32 v[18:19], v[62:63], v[50:51]
; #define LAS __attribute__((address_space(3)))
;     __device__ __forceinline__ void run(f32x4 (&acc)[2][2][4][2], const pg8::Unit& u, int wr, int wc, int fr_, int fq_, int buf) const {
;     ...
;                     for (int bj = 0; bj < 2; ++bj) { const int col = colg + 128 * bj + 4 * n + 2 * eh;
;                         const int tcol = 128 * bj + colL + 4 * n + 2 * eh;
;                         const f32x2 w0 = *(const LAS f32x2*)(TB + tcol), w1 = *(const LAS f32x2*)(TB + 256 + tcol), w2 = *(const LAS f32x2*)(TB + 512 + tcol), cb = *(const LAS f32x2*)(TB + 768 + tcol);
;                         const int ia = rb > 0 ? (rb - 1) * 2 + 1 : 0, ib = rb < 3 ? (rb + 1) * 2 : 7;
;                         const f32x2 above = *(const LAS f32x2*)(X + ia * 256 + 128 * bj + colL + 4 * n + 2 * eh);
;                         const f32x2 below = *(const LAS f32x2*)(X + ib * 256 + 128 * bj + colL + 4 * n + 2 * eh);
;                         f32x2 U0, U1, U2, U3;
;                         U0[0] = acc[ai][bj][0][n][2 * eh]; U0[1] = acc[ai][bj][0][n][2 * eh + 1]; U1[0] = acc[ai][bj][1][n][2 * eh]; U1[1] = acc[ai][bj][1][n][2 * eh + 1];
;                         U2[0] = acc[ai][bj][2][n][2 * eh]; U2[1] = acc[ai][bj][2][n][2 * eh + 1]; U3[0] = acc[ai][bj][3][n][2 * eh]; U3[1] = acc[ai][bj][3][n][2 * eh + 1];
;                         f32x2 up0, dn3;
;                         up0[0] = dpp_shr1(above[0], U3[0]); up0[1] = dpp_shr1(above[1], U3[1]); dn3[0] = dpp_shl1(below[0], U0[0]); dn3[1] = dpp_shl1(below[1], U0[1]);
;                         f32x2 cv[4];
;                         cv[0] = w2 * U1 + (w1 * U0 + (w0 * up0 + cb));
;                         cv[1] = w2 * U2 + (w1 * U1 + (w0 * U0 + cb));
;                         cv[2] = w2 * U3 + (w1 * U2 + (w0 * U1 + cb));
;                         cv[3] = w2 * dn3 + (w1 * U3 + (w0 * U2 + cb));
;                         if (bj == 0) {
; #pragma unroll
;                             for (int m = 0; m < 4; ++m) {
;                                 f32x2 ex; ex[0] = __builtin_amdgcn_exp2f(-cv[m][0]); ex[1] = __builtin_amdgcn_exp2f(-cv[m][1]);
;                                 const f32x2 den = ex + 1.0f; f32x2 rc; rc[0] = __builtin_amdgcn_rcpf(den[0]); rc[1] = __builtin_amdgcn_rcpf(den[1]);
;                                 sg[m] = cv[m] * rc; }
;                         } else {
; #pragma unroll
	v_mov_b32_dpp v88, v4 row_shr:1 row_mask:0xf bank_mask:0xf
	v_mov_b32_dpp v89, v5 row_shr:1 row_mask:0xf bank_mask:0xf
	v_cvt_pk_bf16_f32 v25, v24, v25
	v_pk_mul_f32 v[40:41], v[92:93], v[40:41]
	v_cvt_pk_bf16_f32 v24, v18, v19
	v_pk_mul_f32 v[18:19], v[52:53], v[38:39]
	v_cvt_pk_bf16_f32 v41, v40, v41
	v_cvt_pk_bf16_f32 v40, v18, v19
	v_pk_fma_f32 v[18:19], v[48:49], v[28:29], v[12:13]
	v_pk_fma_f32 v[38:39], v[190:191], v[28:29], v[12:13]
	v_pk_fma_f32 v[50:51], v[172:173], v[28:29], v[12:13]
	v_pk_fma_f32 v[12:13], v[28:29], v[88:89], v[12:13]
	v_mov_b32_dpp v98, v172 row_shl:1 row_mask:0xf bank_mask:0xf
	v_pk_fma_f32 v[12:13], v[172:173], v[36:37], v[12:13]
	v_mov_b32_dpp v99, v173 row_shl:1 row_mask:0xf bank_mask:0xf
	v_pk_fma_f32 v[18:19], v[4:5], v[36:37], v[18:19]
	v_pk_fma_f32 v[38:39], v[48:49], v[36:37], v[38:39]
	v_pk_fma_f32 v[50:51], v[190:191], v[36:37], v[50:51]
	v_pk_fma_f32 v[12:13], v[190:191], v[16:17], v[12:13]
	v_pk_fma_f32 v[18:19], v[16:17], v[98:99], v[18:19]
	v_pk_fma_f32 v[4:5], v[4:5], v[16:17], v[38:39]
	v_pk_fma_f32 v[48:49], v[48:49], v[16:17], v[50:51]
	v_exp_f32_e64 v16, -v12
	v_exp_f32_e64 v17, -v13
	v_exp_f32_e64 v22, -v18
	v_exp_f32_e64 v23, -v19
	v_exp_f32_e64 v38, -v4
	v_pk_add_f32 v[16:17], v[16:17], 1.0 op_sel_hi:[1,0]
	v_exp_f32_e64 v39, -v5
	v_rcp_f32_e32 v16, v16
	v_rcp_f32_e32 v17, v17
	v_pk_add_f32 v[22:23], v[22:23], 1.0 op_sel_hi:[1,0]
	v_exp_f32_e64 v50, -v48
	v_rcp_f32_e32 v22, v22
	v_rcp_f32_e32 v23, v23
	v_exp_f32_e64 v51, -v49
	v_pk_mul_f32 v[12:13], v[12:13], v[16:17]
	v_pk_fma_f32 v[16:17], v[32:33], v[60:61], v[56:57]
	v_mov_b32_dpp v76, v174 row_shl:1 row_mask:0xf bank_mask:0xf
	v_mov_b32_dpp v77, v175 row_shl:1 row_mask:0xf bank_mask:0xf
	v_pk_fma_f32 v[16:17], v[8:9], v[72:73], v[16:17]
	v_pk_add_f32 v[38:39], v[38:39], 1.0 op_sel_hi:[1,0]
	v_pk_mul_f32 v[18:19], v[18:19], v[22:23]
	v_pk_fma_f32 v[16:17], v[44:45], v[76:77], v[16:17]
	v_rcp_f32_e32 v38, v38
	v_rcp_f32_e32 v39, v39
	v_pk_add_f32 v[28:29], v[50:51], 1.0 op_sel_hi:[1,0]
	v_pk_mul_f32 v[16:17], v[16:17], v[18:19]
	v_rcp_f32_e32 v28, v28
	v_rcp_f32_e32 v29, v29
	v_cvt_pk_bf16_f32 v93, v16, v17
	v_pk_fma_f32 v[16:17], v[188:189], v[60:61], v[56:57]
	v_mov_b32_dpp v68, v8 row_shr:1 row_mask:0xf bank_mask:0xf
	v_pk_fma_f32 v[16:17], v[32:33], v[72:73], v[16:17]
	v_mov_b32_dpp v69, v9 row_shr:1 row_mask:0xf bank_mask:0xf
	v_pk_fma_f32 v[8:9], v[8:9], v[44:45], v[16:17]
	v_pk_fma_f32 v[16:17], v[174:175], v[60:61], v[56:57]
	v_pk_mul_f32 v[4:5], v[4:5], v[38:39]
	v_pk_fma_f32 v[16:17], v[188:189], v[72:73], v[16:17]
	v_pk_fma_f32 v[18:19], v[60:61], v[68:69], v[56:57]
	v_pk_mul_f32 v[22:23], v[48:49], v[28:29]
	v_pk_fma_f32 v[16:17], v[32:33], v[44:45], v[16:17]
	v_pk_fma_f32 v[18:19], v[174:175], v[72:73], v[18:19]
	v_pk_mul_f32 v[4:5], v[4:5], v[8:9]
	v_pk_fma_f32 v[28:29], v[188:189], v[44:45], v[18:19]
	v_cvt_pk_bf16_f32 v19, v4, v5
	v_pk_mul_f32 v[4:5], v[22:23], v[16:17]
	v_mov_b32_dpp v86, v2 row_shr:1 row_mask:0xf bank_mask:0xf
	v_cvt_pk_bf16_f32 v23, v4, v5
	v_pk_mul_f32 v[4:5], v[28:29], v[12:13]
	v_pk_fma_f32 v[12:13], v[184:185], v[26:27], v[10:11]
	v_cvt_pk_bf16_f32 v39, v4, v5
	v_pk_fma_f32 v[4:5], v[46:47], v[26:27], v[10:11]
	v_pk_fma_f32 v[12:13], v[46:47], v[34:35], v[12:13]
	v_mov_b32_dpp v87, v3 row_shr:1 row_mask:0xf bank_mask:0xf
	v_pk_fma_f32 v[4:5], v[2:3], v[34:35], v[4:5]
	v_pk_fma_f32 v[2:3], v[2:3], v[14:15], v[12:13]
	v_mov_b32_dpp v96, v168 row_shl:1 row_mask:0xf bank_mask:0xf
	v_mov_b32_dpp v97, v169 row_shl:1 row_mask:0xf bank_mask:0xf
	v_exp_f32_e64 v12, -v2
	v_exp_f32_e64 v13, -v3
	v_pk_fma_f32 v[4:5], v[14:15], v[96:97], v[4:5]
	v_pk_fma_f32 v[16:17], v[168:169], v[26:27], v[10:11]
	v_exp_f32_e64 v8, -v4
	v_exp_f32_e64 v9, -v5
	v_pk_add_f32 v[12:13], v[12:13], 1.0 op_sel_hi:[1,0]
	v_pk_fma_f32 v[16:17], v[184:185], v[34:35], v[16:17]
	v_rcp_f32_e32 v12, v12
; __device__ __forceinline__ unsigned cvt_pk(float lo, float hi) { f32x2_t v = {lo, hi}; bf16x2_t b = __builtin_convertvector(v, bf16x2_t); return __builtin_bit_cast(unsigned, b); }
; __device__ __forceinline__ size_t blk_off(int row, int col, int K) { return ((size_t)((row >> 8) * (K >> 6) + (col >> 6)) << 14) + (size_t)(((row & 255) << 6) + (col & 63)); }
;     __device__ __forceinline__ void run(f32x4 (&acc)[2][2][4][2], const pg8::Unit& u, int wr, int wc, int fr_, int fq_, int buf) const {
;     ...
;                         cv[0] = w2 * U1 + (w1 * U0 + (w0 * up0 + cb));
;                         cv[1] = w2 * U2 + (w1 * U1 + (w0 * U0 + cb));
;                         cv[2] = w2 * U3 + (w1 * U2 + (w0 * U1 + cb));
;                         cv[3] = w2 * dn3 + (w1 * U3 + (w0 * U2 + cb));
;                         if (bj == 0) {
; #pragma unroll
;                             for (int m = 0; m < 4; ++m) {
;                                 f32x2 ex; ex[0] = __builtin_amdgcn_exp2f(-cv[m][0]); ex[1] = __builtin_amdgcn_exp2f(-cv[m][1]);
;                                 const f32x2 den = ex + 1.0f; f32x2 rc; rc[0] = __builtin_amdgcn_rcpf(den[0]); rc[1] = __builtin_amdgcn_rcpf(den[1]);
;                                 sg[m] = cv[m] * rc; }
;                         } else {
; #pragma unroll
;                             for (int m = 0; m < 4; ++m) { const f32x2 av = sg[m] * cv[m]; pk[m][n][eh] = cvt_pk(av[0], av[1]); }
;                         }
;                     }
;                 }
;             }
; #pragma unroll
;             for (int m = 0; m < 4; ++m) { const int tr = 128 * ai + 64 * wr + 4 * fr + m; v4u w; w.x = pk[m][0][0]; w.y = pk[m][0][1]; w.z = pk[m][1][0]; w.w = pk[m][1][1];
;                 __builtin_nontemporal_store(w, (v4u*)(act + blk_off(u.pm * 256 + tr, u.pn * 128 + colL, FF))); }
	v_rcp_f32_e32 v13, v13
	v_pk_add_f32 v[8:9], v[8:9], 1.0 op_sel_hi:[1,0]
	v_pk_fma_f32 v[10:11], v[26:27], v[86:87], v[10:11]
	v_rcp_f32_e32 v8, v8
	v_rcp_f32_e32 v9, v9
	v_pk_fma_f32 v[16:17], v[46:47], v[14:15], v[16:17]
	v_pk_fma_f32 v[10:11], v[168:169], v[34:35], v[10:11]
	v_exp_f32_e64 v28, -v16
	v_exp_f32_e64 v29, -v17
	v_pk_fma_f32 v[10:11], v[184:185], v[14:15], v[10:11]
	v_pk_mul_f32 v[2:3], v[2:3], v[12:13]
	v_exp_f32_e64 v14, -v10
	v_exp_f32_e64 v15, -v11
	v_pk_fma_f32 v[12:13], v[30:31], v[58:59], v[54:55]
	v_mov_b32_dpp v74, v170 row_shl:1 row_mask:0xf bank_mask:0xf
	v_mov_b32_dpp v75, v171 row_shl:1 row_mask:0xf bank_mask:0xf
	v_pk_fma_f32 v[12:13], v[6:7], v[70:71], v[12:13]
	v_pk_mul_f32 v[4:5], v[4:5], v[8:9]
	v_pk_fma_f32 v[12:13], v[42:43], v[74:75], v[12:13]
	v_pk_add_f32 v[26:27], v[28:29], 1.0 op_sel_hi:[1,0]
	v_pk_mul_f32 v[4:5], v[12:13], v[4:5]
	v_rcp_f32_e32 v26, v26
	v_rcp_f32_e32 v27, v27
	v_pk_add_f32 v[14:15], v[14:15], 1.0 op_sel_hi:[1,0]
	v_cvt_pk_bf16_f32 v92, v4, v5
	v_pk_fma_f32 v[4:5], v[182:183], v[58:59], v[54:55]
	v_rcp_f32_e32 v14, v14
	v_rcp_f32_e32 v15, v15
	v_pk_fma_f32 v[4:5], v[30:31], v[70:71], v[4:5]
	v_mov_b32_dpp v66, v6 row_shr:1 row_mask:0xf bank_mask:0xf
	v_mov_b32_dpp v67, v7 row_shr:1 row_mask:0xf bank_mask:0xf
	v_pk_fma_f32 v[4:5], v[6:7], v[42:43], v[4:5]
	v_pk_fma_f32 v[6:7], v[170:171], v[58:59], v[54:55]
	v_pk_fma_f32 v[12:13], v[58:59], v[66:67], v[54:55]
	v_pk_fma_f32 v[6:7], v[182:183], v[70:71], v[6:7]
	v_pk_mul_f32 v[8:9], v[16:17], v[26:27]
	v_pk_fma_f32 v[6:7], v[30:31], v[42:43], v[6:7]
	v_pk_fma_f32 v[12:13], v[170:171], v[70:71], v[12:13]
	v_pk_mul_f32 v[2:3], v[2:3], v[4:5]
	v_pk_mul_f32 v[10:11], v[10:11], v[14:15]
	v_pk_fma_f32 v[12:13], v[182:183], v[42:43], v[12:13]
	v_cvt_pk_bf16_f32 v18, v2, v3
	v_pk_mul_f32 v[2:3], v[8:9], v[6:7]
	v_add_u32_e32 v4, 0x80, v238
	v_cvt_pk_bf16_f32 v22, v2, v3
	v_pk_mul_f32 v[2:3], v[12:13], v[10:11]
	s_movk_i32 s1, 0x3f40
	v_cvt_pk_bf16_f32 v38, v2, v3
	v_add_u32_e32 v2, s0, v4
	v_lshrrev_b32_e32 v2, 8, v2
	v_mad_i32_i24 v2, v2, 44, v237
	v_ashrrev_i32_e32 v3, 31, v2
	v_lshlrev_b32_e32 v4, 6, v4
	v_and_or_b32 v4, v4, s82, v236
	v_lshlrev_b64 v[2:3], 15, v[2:3]
	v_lshl_add_u64 v[2:3], s[16:17], 0, v[2:3]
	v_lshlrev_b32_e32 v162, 1, v4
	v_lshl_add_u64 v[2:3], v[2:3], 0, v[162:163]
	v_add_u32_e32 v4, 0x81, v238
	global_store_dwordx4 v[2:3], v[38:41], off
	v_add_u32_e32 v2, s0, v4
	v_lshrrev_b32_e32 v2, 8, v2
	v_mad_i32_i24 v2, v2, 44, v237
	v_ashrrev_i32_e32 v3, 31, v2
	v_lshlrev_b32_e32 v4, 6, v4
	v_and_or_b32 v4, v4, s1, v236
	v_lshlrev_b64 v[2:3], 15, v[2:3]
	v_lshl_add_u64 v[2:3], s[16:17], 0, v[2:3]
	v_lshlrev_b32_e32 v162, 1, v4
	v_lshl_add_u64 v[2:3], v[2:3], 0, v[162:163]
	v_add_u32_e32 v4, 0x82, v238
	global_store_dwordx4 v[2:3], v[22:25], off
	v_add_u32_e32 v2, s0, v4
	v_lshrrev_b32_e32 v2, 8, v2
	v_mad_i32_i24 v2, v2, 44, v237
	v_ashrrev_i32_e32 v3, 31, v2
	v_lshlrev_b32_e32 v4, 6, v4
	s_movk_i32 s1, 0x3f80
	v_and_or_b32 v4, v4, s1, v236
	v_lshlrev_b64 v[2:3], 15, v[2:3]
	v_lshl_add_u64 v[2:3], s[16:17], 0, v[2:3]
	v_lshlrev_b32_e32 v162, 1, v4
	v_lshl_add_u64 v[2:3], v[2:3], 0, v[162:163]
	v_add_u32_e32 v4, 0x83, v238
	global_store_dwordx4 v[2:3], v[18:21], off
	v_add_u32_e32 v2, s0, v4
	v_lshrrev_b32_e32 v2, 8, v2
	v_mad_i32_i24 v2, v2, 44, v237
	v_ashrrev_i32_e32 v3, 31, v2
	v_lshlrev_b32_e32 v4, 6, v4
	s_movk_i32 s0, 0x3fc0
	v_and_or_b32 v4, v4, s0, v236
	v_lshlrev_b64 v[2:3], 15, v[2:3]
	v_lshl_add_u64 v[2:3], s[16:17], 0, v[2:3]
	v_lshlrev_b32_e32 v162, 1, v4
	v_lshl_add_u64 v[2:3], v[2:3], 0, v[162:163]
	s_mov_b64 s[0:1], -1
	global_store_dwordx4 v[2:3], v[92:95], off
	s_cbranch_vccnz .LBB0_528
	s_andn2_b64 vcc, exec, s[24:25]
	s_cbranch_vccnz .LBB0_559
	s_add_i32 s6, s36, s70
	s_cmp_lt_i32 s11, 1
	s_cbranch_scc1 .LBB0_553
	s_cmp_gt_i32 s11, 4
	s_cbranch_scc0 .LBB0_550
	s_mov_b64 s[0:1], 0
